# v11 plus nt on rms x loads and on the f32 residual base loads of the four residual epilogues
# speedup vs baseline: 1.0127x; 1.0127x over previous
; __device__ __forceinline__ void rms_phase(const float* X, const float* g, bf16_t* H, int gw, int NGW, int lane) {
;     for (int m = gw; m < M; m += 2 * NGW) {
;         const int m2 = m + NGW; const bool two = m2 < M;
;         const f32x4* xa = (const f32x4*)(X + (size_t)m * DM) + lane; const f32x4* xb = (const f32x4*)(X + (size_t)(two ? m2 : m) * DM) + lane; const f32x4* gr = (const f32x4*)g + lane;
;         f32x4 va[8], vb[8]; float sa = 0.f, sb = 0.f;
; #pragma unroll
;         for (int j = 0; j < 8; ++j) { va[j] = xa[64 * j]; vb[j] = xb[64 * j]; }
; #pragma unroll
;         for (int j = 0; j < 8; ++j) { sa += (va[j].x * va[j].x + va[j].y * va[j].y) + (va[j].z * va[j].z + va[j].w * va[j].w); sb += (vb[j].x * vb[j].x + vb[j].y * vb[j].y) + (vb[j].z * vb[j].z + vb[j].w * vb[j].w); }
;         const float ra = 1.0f / sqrtf(wave_sum(sa) * (1.0f / DM) + EPS), rb = 1.0f / sqrtf(wave_sum(sb) * (1.0f / DM) + EPS);
.LBB0_64:
	s_ashr_i32 s7, s6, 31
	s_lshl_b64 s[4:5], s[6:7], 13
	v_lshl_add_u64 v[0:1], v[68:69], 0, s[4:5]
	s_add_i32 s8, s6, s69
	global_load_dwordx4 v[56:59], v[0:1], off nt
	global_load_dwordx4 v[48:51], v[0:1], off offset:1024 nt
	global_load_dwordx4 v[40:43], v[0:1], off offset:2048 nt
	global_load_dwordx4 v[32:35], v[0:1], off offset:3072 nt
	v_add_co_u32_e32 v0, vcc, s12, v0
	s_cmpk_lt_i32 s8, 0x4000
	s_nop 0
	v_addc_co_u32_e32 v1, vcc, 0, v1, vcc
	s_cselect_b64 s[10:11], -1, 0
	global_load_dwordx4 v[24:27], v[0:1], off nt
	global_load_dwordx4 v[20:23], v[0:1], off offset:1024 nt
	s_and_b64 s[4:5], s[10:11], exec
	s_cselect_b32 s4, s8, s6
	s_ashr_i32 s5, s4, 31
	s_lshl_b64 s[4:5], s[4:5], 13
	v_lshl_add_u64 v[2:3], v[68:69], 0, s[4:5]
	global_load_dwordx4 v[60:63], v[2:3], off nt
	global_load_dwordx4 v[52:55], v[2:3], off offset:1024 nt
	global_load_dwordx4 v[44:47], v[2:3], off offset:2048 nt
	global_load_dwordx4 v[36:39], v[2:3], off offset:3072 nt
	global_load_dwordx4 v[4:7], v[0:1], off offset:3072 nt
	global_load_dwordx4 v[12:15], v[0:1], off offset:2048 nt
	v_add_co_u32_e32 v64, vcc, s12, v2
	s_lshl_b64 s[14:15], s[6:7], 12
	s_nop 0
	v_addc_co_u32_e32 v65, vcc, 0, v3, vcc
	global_load_dwordx4 v[28:31], v[64:65], off nt
	global_load_dwordx4 v[16:19], v[64:65], off offset:1024 nt
	global_load_dwordx4 v[8:11], v[64:65], off offset:2048 nt
	global_load_dwordx4 v[0:3], v[64:65], off offset:3072 nt
	s_ashr_i32 s9, s8, 31
	s_lshl_b64 s[18:19], s[8:9], 12
	s_cmpk_gt_i32 s8, 0x3fff
	s_waitcnt vmcnt(15)
	v_mov_b32_e32 v66, v57
	s_waitcnt vmcnt(14)
	v_mov_b32_e32 v67, v49
	v_mov_b32_e32 v86, v59
	v_mov_b32_e32 v87, v51
	v_mov_b32_e32 v64, v56
	v_mov_b32_e32 v65, v48
	v_mov_b32_e32 v82, v58
	v_mov_b32_e32 v83, v50
	s_waitcnt vmcnt(13)
	v_pk_mul_f32 v[88:89], v[42:43], v[42:43]
	v_pk_mul_f32 v[98:99], v[40:41], v[40:41]
	s_waitcnt vmcnt(12)
	v_mul_f32_e32 v84, v33, v33
	v_mul_f32_e32 v100, v35, v35
	v_pk_mul_f32 v[66:67], v[66:67], v[66:67]
	v_pk_mul_f32 v[86:87], v[86:87], v[86:87]
	v_pk_mov_b32 v[102:103], v[98:99], v[88:89] op_sel:[1,0]
	v_mov_b32_e32 v99, v89
	s_waitcnt vmcnt(11)
	v_mul_f32_e32 v109, v26, v26
	v_mul_f32_e32 v110, v27, v27
	v_pk_fma_f32 v[88:89], v[32:33], v[32:33], v[84:85] op_sel_hi:[1,1,0]
	v_pk_fma_f32 v[100:101], v[34:35], v[34:35], v[100:101] op_sel_hi:[1,1,0]
	v_pk_fma_f32 v[64:65], v[64:65], v[64:65], v[66:67]
	v_pk_fma_f32 v[66:67], v[82:83], v[82:83], v[86:87]
	v_pk_add_f32 v[82:83], v[102:103], v[98:99]
	v_mov_b32_e32 v89, v109
	v_mov_b32_e32 v101, v110
	v_pk_add_f32 v[64:65], v[64:65], v[66:67]
	v_mul_f32_e32 v97, v24, v24
	v_mul_f32_e32 v108, v25, v25
	v_pk_add_f32 v[66:67], v[82:83], v[82:83] op_sel:[0,1] op_sel_hi:[1,0]
	v_pk_add_f32 v[82:83], v[88:89], v[100:101]
	v_pk_add_f32 v[64:65], v[64:65], v[64:65] op_sel:[0,1] op_sel_hi:[1,0]
	s_waitcnt vmcnt(9)
	v_mul_f32_e32 v84, v61, v61
	v_mul_f32_e32 v86, v63, v63
	s_waitcnt vmcnt(8)
	v_mul_f32_e32 v87, v53, v53
	v_mul_f32_e32 v88, v55, v55
	v_mov_b32_e32 v67, v108
	v_mov_b32_e32 v65, v97
	s_waitcnt vmcnt(7)
	v_mul_f32_e32 v89, v45, v45
	v_mul_f32_e32 v97, v47, v47
	v_fmac_f32_e32 v84, v60, v60
	v_fmac_f32_e32 v86, v62, v62
	v_fmac_f32_e32 v87, v52, v52
	v_fmac_f32_e32 v88, v54, v54
	s_waitcnt vmcnt(6)
	v_mul_f32_e32 v98, v37, v37
	v_mul_f32_e32 v99, v39, v39
	v_pk_add_f32 v[64:65], v[64:65], v[66:67]
	v_fmac_f32_e32 v89, v44, v44
	v_fmac_f32_e32 v97, v46, v46
	v_add_f32_e32 v66, v84, v86
	v_add_f32_e32 v67, v87, v88
	v_fmac_f32_e32 v98, v36, v36
	v_fmac_f32_e32 v99, v38, v38
	v_pk_add_f32 v[64:65], v[64:65], v[82:83]
	v_add_f32_e32 v82, v89, v97
	v_add_f32_e32 v66, v66, v67
	v_pk_mul_f32 v[104:105], v[22:23], v[22:23]
	v_pk_mul_f32 v[106:107], v[20:21], v[20:21]
	v_add_f32_e32 v83, v98, v99
	v_add_f32_e32 v66, v66, v82
	v_add_f32_e32 v84, v66, v83
	v_pk_mov_b32 v[66:67], v[106:107], v[104:105] op_sel:[1,0]
	v_mov_b32_e32 v107, v105
	v_pk_add_f32 v[66:67], v[66:67], v[106:107]
	s_waitcnt vmcnt(5)
	v_mul_f32_e32 v82, v4, v4
	v_mul_f32_e32 v83, v5, v5
	v_pk_add_f32 v[64:65], v[64:65], v[64:65] op_sel:[0,1] op_sel_hi:[1,0]
	v_pk_add_f32 v[66:67], v[66:67], v[66:67] op_sel:[0,1] op_sel_hi:[1,0]
	v_mov_b32_e32 v65, v82
	v_mov_b32_e32 v67, v83
	v_pk_add_f32 v[64:65], v[64:65], v[66:67]
	s_waitcnt vmcnt(4)
	v_mul_f32_e32 v66, v13, v13
	v_mul_f32_e32 v82, v15, v15
	v_mul_f32_e32 v86, v6, v6
	v_mul_f32_e32 v87, v7, v7
	v_pk_fma_f32 v[66:67], v[12:13], v[12:13], v[66:67] op_sel_hi:[1,1,0]
	v_pk_fma_f32 v[82:83], v[14:15], v[14:15], v[82:83] op_sel_hi:[1,1,0]
	v_mov_b32_e32 v67, v86
	v_mov_b32_e32 v83, v87
	v_pk_add_f32 v[66:67], v[66:67], v[82:83]
	s_waitcnt vmcnt(2)
; __device__ __forceinline__ unsigned cvt_pk_bf16(float lo, float hi) { f32x2_t f = {lo, hi}; bf16x2_t r = __builtin_convertvector(f, bf16x2_t); return __builtin_bit_cast(unsigned, r); }
; __device__ __forceinline__ void rms_phase(const float* X, const float* g, bf16_t* H, int gw, int NGW, int lane) {
;     ...
;         const float ra = 1.0f / sqrtf(wave_sum(sa) * (1.0f / DM) + EPS), rb = 1.0f / sqrtf(wave_sum(sb) * (1.0f / DM) + EPS);
;         u32x2* oa = (u32x2*)(H + (size_t)m * DM) + lane; u32x2* ob = (u32x2*)(H + (size_t)m2 * DM) + lane;
; #pragma unroll
;         for (int j = 0; j < 8; ++j) { const f32x4 gg = gr[64 * j]; u32x2 w; w.x = cvt_pk_bf16(va[j].x * ra * gg.x, va[j].y * ra * gg.y); w.y = cvt_pk_bf16(va[j].z * ra * gg.z, va[j].w * ra * gg.w); oa[64 * j] = w;
;             if (two) { u32x2 w2; w2.x = cvt_pk_bf16(vb[j].x * rb * gg.x, vb[j].y * rb * gg.y); w2.y = cvt_pk_bf16(vb[j].z * rb * gg.z, vb[j].w * rb * gg.w); ob[64 * j] = w2; } }
	v_mul_f32_e32 v82, v19, v19
	v_pk_add_f32 v[64:65], v[64:65], v[66:67]
	v_mul_f32_e32 v66, v29, v29
	v_add_f32_e32 v64, v64, v65
	ds_bpermute_b32 v65, v85, v64
	v_mul_f32_e32 v67, v31, v31
	v_fmac_f32_e32 v66, v28, v28
	v_fmac_f32_e32 v67, v30, v30
	v_add_f32_e32 v66, v66, v67
	s_waitcnt lgkmcnt(0)
	v_add_f32_e32 v64, v64, v65
	ds_bpermute_b32 v65, v90, v64
	v_mul_f32_e32 v67, v17, v17
	v_fmac_f32_e32 v67, v16, v16
	v_fmac_f32_e32 v82, v18, v18
	v_add_f32_e32 v66, v84, v66
	s_waitcnt lgkmcnt(0)
	v_add_f32_e32 v64, v64, v65
	ds_bpermute_b32 v65, v91, v64
	v_add_f32_e32 v67, v67, v82
	v_add_f32_e32 v66, v66, v67
	s_waitcnt vmcnt(1)
	v_mul_f32_e32 v67, v9, v9
	v_mul_f32_e32 v82, v11, v11
	s_waitcnt lgkmcnt(0)
	v_add_f32_e32 v64, v64, v65
	ds_bpermute_b32 v65, v93, v64
	v_fmac_f32_e32 v67, v8, v8
	v_fmac_f32_e32 v82, v10, v10
	v_add_f32_e32 v67, v67, v82
	v_add_f32_e32 v66, v66, v67
	s_waitcnt lgkmcnt(0)
	v_add_f32_e32 v64, v64, v65
	ds_bpermute_b32 v65, v94, v64
	s_waitcnt vmcnt(0)
	v_mul_f32_e32 v67, v1, v1
	v_mul_f32_e32 v82, v3, v3
	v_fmac_f32_e32 v67, v0, v0
	v_fmac_f32_e32 v82, v2, v2
	s_waitcnt lgkmcnt(0)
	v_add_f32_e32 v64, v64, v65
	ds_bpermute_b32 v65, v95, v64
	v_add_f32_e32 v67, v67, v82
	v_add_f32_e32 v82, v66, v67
	ds_bpermute_b32 v86, v85, v82
	s_waitcnt lgkmcnt(1)
	v_add_f32_e32 v64, v64, v65
	v_fmamk_f32 v83, v64, 0x3a000000, v92
	s_nop 1
	v_mov_b64_e32 v[64:65], v[140:141]
	v_mov_b64_e32 v[66:67], v[142:143]
	s_waitcnt lgkmcnt(0)
	v_add_f32_e32 v82, v82, v86
	ds_bpermute_b32 v86, v90, v82
	v_mul_f32_e32 v84, 0x4f800000, v83
	v_cmp_gt_f32_e32 vcc, s13, v83
	s_waitcnt lgkmcnt(0)
	v_add_f32_e32 v82, v82, v86
	ds_bpermute_b32 v86, v91, v82
	v_cndmask_b32_e32 v83, v83, v84, vcc
	v_sqrt_f32_e32 v84, v83
	s_waitcnt lgkmcnt(0)
	v_add_f32_e32 v82, v82, v86
	ds_bpermute_b32 v86, v93, v82
	v_add_u32_e32 v87, -1, v84
	v_fma_f32 v88, -v87, v84, v83
	v_cmp_ge_f32_e64 s[4:5], 0, v88
	v_add_u32_e32 v88, 1, v84
	s_waitcnt lgkmcnt(0)
	v_add_f32_e32 v82, v82, v86
	ds_bpermute_b32 v86, v94, v82
	v_cndmask_b32_e64 v87, v84, v87, s[4:5]
	v_fma_f32 v84, -v88, v84, v83
	v_cmp_lt_f32_e64 s[4:5], 0, v84
	s_waitcnt lgkmcnt(0)
	v_add_f32_e32 v82, v82, v86
	v_cndmask_b32_e64 v84, v87, v88, s[4:5]
	v_mul_f32_e32 v87, 0x37800000, v84
	ds_bpermute_b32 v86, v95, v82
	v_cndmask_b32_e32 v84, v84, v87, vcc
	v_cmp_class_f32_e32 vcc, v83, v96
	s_waitcnt lgkmcnt(0)
	v_add_f32_e32 v82, v82, v86
	v_cndmask_b32_e32 v83, v84, v83, vcc
	v_div_scale_f32 v84, s[4:5], v83, v83, 1.0
	v_rcp_f32_e32 v87, v84
	v_fmamk_f32 v82, v82, 0x3a000000, v92
	v_mul_f32_e32 v86, 0x4f800000, v82
	v_cmp_gt_f32_e64 s[4:5], s13, v82
	v_fma_f32 v88, -v84, v87, 1.0
	v_fmac_f32_e32 v87, v88, v87
	v_cndmask_b32_e64 v82, v82, v86, s[4:5]
	v_div_scale_f32 v88, vcc, 1.0, v83, 1.0
	v_sqrt_f32_e32 v86, v82
	v_mul_f32_e32 v89, v88, v87
	v_fma_f32 v97, -v84, v89, v88
	v_fmac_f32_e32 v89, v97, v87
	v_fma_f32 v84, -v84, v89, v88
	v_add_u32_e32 v88, -1, v86
	v_fma_f32 v97, -v88, v86, v82
	v_cmp_ge_f32_e64 s[6:7], 0, v97
	v_add_u32_e32 v97, 1, v86
	v_div_fmas_f32 v84, v84, v87, v89
	v_cndmask_b32_e64 v88, v86, v88, s[6:7]
	v_fma_f32 v86, -v97, v86, v82
	v_cmp_lt_f32_e64 s[6:7], 0, v86
	s_nop 1
	v_cndmask_b32_e64 v86, v88, v97, s[6:7]
	v_mul_f32_e32 v88, 0x37800000, v86
	v_cndmask_b32_e64 v86, v86, v88, s[4:5]
	v_cmp_class_f32_e64 s[4:5], v82, v96
	v_div_fixup_f32 v88, v84, v83, 1.0
	v_pk_mul_f32 v[56:57], v[56:57], v[88:89] op_sel_hi:[1,0]
	v_cndmask_b32_e64 v82, v86, v82, s[4:5]
	v_div_scale_f32 v86, s[4:5], v82, v82, 1.0
	v_rcp_f32_e32 v97, v86
	v_pk_mul_f32 v[58:59], v[58:59], v[88:89] op_sel_hi:[1,0]
	v_fma_f32 v83, -v86, v97, 1.0
	v_fmac_f32_e32 v97, v83, v97
	v_div_scale_f32 v83, vcc, 1.0, v82, 1.0
	v_mul_f32_e32 v84, v83, v97
	v_fma_f32 v87, -v86, v84, v83
	v_fmac_f32_e32 v84, v87, v97
	v_fma_f32 v83, -v86, v84, v83
	v_div_fmas_f32 v83, v83, v97, v84
	v_pk_mul_f32 v[56:57], v[64:65], v[56:57]
	v_pk_mul_f32 v[58:59], v[66:67], v[58:59]
	v_div_fixup_f32 v84, v83, v82, 1.0
	v_lshl_add_u64 v[86:87], v[72:73], 0, s[14:15]
	v_lshl_add_u64 v[82:83], v[72:73], 0, s[18:19]
	v_cvt_pk_bf16_f32 v56, v56, v57
	v_cvt_pk_bf16_f32 v57, v58, v59
	global_store_dwordx2 v[86:87], v[56:57], off
	s_cbranch_scc1 .LBB0_66
	v_pk_mul_f32 v[56:57], v[60:61], v[84:85] op_sel_hi:[1,0]
	v_pk_mul_f32 v[58:59], v[62:63], v[84:85] op_sel_hi:[1,0]
	v_pk_mul_f32 v[56:57], v[64:65], v[56:57]
	v_pk_mul_f32 v[58:59], v[66:67], v[58:59]
	v_cvt_pk_bf16_f32 v56, v56, v57
	v_cvt_pk_bf16_f32 v57, v58, v59
	global_store_dwordx2 v[82:83], v[56:57], off

; __device__ __forceinline__ unsigned cvt_pk_bf16(float lo, float hi) { f32x2_t f = {lo, hi}; bf16x2_t r = __builtin_convertvector(f, bf16x2_t); return __builtin_bit_cast(unsigned, r); }
;     __device__ __forceinline__ void operator()(f32x4 (&acc)[2][2][4][2], const Unit& u, int wr, int wc, int fr, int fq) const {
;         const int row0 = u.pm * BM + wr * 64 + fr; const int col0 = u.pn * BM + wc * 32 + 4 * fq;
; #pragma unroll
;         for (int ai = 0; ai < 2; ++ai)
; #pragma unroll
;             for (int m = 0; m < 4; ++m) { const size_t off = (size_t)(row0 + ai * HALF + m * 16) * ldc + col0;
; #pragma unroll
;                 for (int bj = 0; bj < 2; ++bj)
; #pragma unroll
;                     for (int n = 0; n < 2; ++n) acc[ai][bj][m][n] += *(const f32x4*)(base + off + bj * HALF + n * 16);
;                 if (m == 3) asm volatile("" : "+v"(acc[ai][0][0][0]), "+v"(acc[ai][0][0][1]), "+v"(acc[ai][1][0][0]), "+v"(acc[ai][1][0][1]), "+v"(acc[ai][0][1][0]), "+v"(acc[ai][0][1][1]), "+v"(acc[ai][1][1][0]), "+v"(acc[ai][1][1][1]),
;                                              "+v"(acc[ai][0][2][0]), "+v"(acc[ai][0][2][1]), "+v"(acc[ai][1][2][0]), "+v"(acc[ai][1][2][1]), "+v"(acc[ai][0][3][0]), "+v"(acc[ai][0][3][1]), "+v"(acc[ai][1][3][0]), "+v"(acc[ai][1][3][1]) :: "memory"); }
;         asm volatile("" ::: "memory");
; #pragma unroll
;         for (int ai = 0; ai < 2; ++ai)
; #pragma unroll
;             for (int m = 0; m < 4; ++m) { const int row = row0 + ai * HALF + m * 16; const size_t off = (size_t)row * ldc + col0; float sq = 0.f;
; #pragma unroll
;                 for (int bj = 0; bj < 2; ++bj)
; #pragma unroll
;                     for (int n = 0; n < 2; ++n) { const f32x4 v = acc[ai][bj][m][n]; *(f32x4*)(out + off + bj * HALF + n * 16) = v;
;                         if (xb) { u32x2e w; w.x = cvt_pk_bf16(v[0], v[1]); w.y = cvt_pk_bf16(v[2], v[3]); *(u32x2e*)(xb + off + bj * HALF + n * 16) = w; sq += (v[0] * v[0] + v[1] * v[1]) + (v[2] * v[2] + v[3] * v[3]); } }
;                 if (xb) { sq += __shfl_xor(sq, 16); sq += __shfl_xor(sq, 32); if (fq == 0) atomicAdd(ss + row, sq); } }
.LBB0_698:
	v_lshl_add_u32 v212, s38, 8, v216
	v_or_b32_e32 v210, 16, v212
	v_or_b32_e32 v208, 32, v212
	v_lshl_or_b32 v196, s40, 8, v218
	v_ashrrev_i32_e32 v213, 31, v212
	v_ashrrev_i32_e32 v211, 31, v210
	v_ashrrev_i32_e32 v209, 31, v208
	v_ashrrev_i32_e32 v197, 31, v196
	v_lshlrev_b64 v[128:129], 13, v[212:213]
	v_lshlrev_b64 v[144:145], 13, v[210:211]
	v_lshlrev_b64 v[160:161], 13, v[208:209]
	v_lshl_add_u64 v[128:129], s[18:19], 0, v[128:129]
	v_lshlrev_b64 v[214:215], 2, v[196:197]
	v_lshl_add_u64 v[144:145], s[18:19], 0, v[144:145]
	v_lshl_add_u64 v[160:161], s[18:19], 0, v[160:161]
	v_or_b32_e32 v204, 48, v212
	v_lshl_add_u64 v[140:141], v[128:129], 0, v[214:215]
	v_lshl_add_u64 v[156:157], v[144:145], 0, v[214:215]
	v_lshl_add_u64 v[172:173], v[160:161], 0, v[214:215]
	v_ashrrev_i32_e32 v205, 31, v204
	global_load_dwordx4 v[128:131], v[140:141], off nt
	global_load_dwordx4 v[132:135], v[140:141], off offset:64 nt
	global_load_dwordx4 v[136:139], v[140:141], off offset:512 nt
	s_nop 0
	global_load_dwordx4 v[140:143], v[140:141], off offset:576 nt
	s_nop 0
	global_load_dwordx4 v[144:147], v[156:157], off nt
	global_load_dwordx4 v[148:151], v[156:157], off offset:64 nt
	global_load_dwordx4 v[152:155], v[156:157], off offset:512 nt
	s_nop 0
	global_load_dwordx4 v[156:159], v[156:157], off offset:576 nt
	s_nop 0
	global_load_dwordx4 v[160:163], v[172:173], off nt
	global_load_dwordx4 v[164:167], v[172:173], off offset:64 nt
	global_load_dwordx4 v[168:171], v[172:173], off offset:512 nt
	global_load_dwordx4 v[180:183], v[172:173], off offset:576 nt
	v_lshlrev_b64 v[172:173], 13, v[204:205]
	v_lshl_add_u64 v[172:173], s[18:19], 0, v[172:173]
	v_lshl_add_u64 v[172:173], v[172:173], 0, v[214:215]
	global_load_dwordx4 v[226:229], v[172:173], off nt
	global_load_dwordx4 v[230:233], v[172:173], off offset:64 nt
	global_load_dwordx4 v[234:237], v[172:173], off offset:512 nt
	global_load_dwordx4 v[238:241], v[172:173], off offset:576 nt
	v_add_u32_e32 v206, 0x80, v212
	v_ashrrev_i32_e32 v207, 31, v206
	v_add_u32_e32 v202, 0x90, v212
	v_lshlrev_b64 v[172:173], 13, v[206:207]
	v_add_u32_e32 v200, 0xa0, v212
	v_lshl_add_u64 v[172:173], s[18:19], 0, v[172:173]
	v_ashrrev_i32_e32 v203, 31, v202
	v_lshl_add_u64 v[242:243], v[172:173], 0, v[214:215]
	v_ashrrev_i32_e32 v201, 31, v200
	v_add_u32_e32 v198, 0xb0, v212
	v_ashrrev_i32_e32 v199, 31, v198
	s_waitcnt vmcnt(0)
	v_pk_add_f32 v[172:173], v[124:125], v[128:129]
	v_pk_add_f32 v[174:175], v[126:127], v[130:131]
	v_pk_add_f32 v[178:179], v[122:123], v[134:135]
	v_pk_add_f32 v[128:129], v[96:97], v[140:141]
	v_pk_add_f32 v[96:97], v[100:101], v[164:165]
	v_lshlrev_b64 v[100:101], 13, v[202:203]
	v_pk_add_f32 v[176:177], v[120:121], v[132:133]
	v_pk_add_f32 v[134:135], v[106:107], v[138:139]
	v_pk_add_f32 v[132:133], v[104:105], v[136:137]
	v_pk_add_f32 v[130:131], v[98:99], v[142:143]
	v_pk_add_f32 v[126:127], v[118:119], v[146:147]
	v_pk_add_f32 v[124:125], v[116:117], v[144:145]
	v_pk_add_f32 v[122:123], v[114:115], v[150:151]
	v_pk_add_f32 v[120:121], v[112:113], v[148:149]
	v_pk_add_f32 v[118:119], v[90:91], v[154:155]
	v_pk_add_f32 v[116:117], v[88:89], v[152:153]
	v_pk_add_f32 v[114:115], v[82:83], v[158:159]
	v_pk_add_f32 v[112:113], v[80:81], v[156:157]
	v_pk_add_f32 v[106:107], v[110:111], v[162:163]
	v_pk_add_f32 v[104:105], v[108:109], v[160:161]
	v_pk_add_f32 v[98:99], v[102:103], v[166:167]
	v_pk_add_f32 v[90:91], v[78:79], v[170:171]
	v_pk_add_f32 v[88:89], v[76:77], v[168:169]
	v_pk_add_f32 v[82:83], v[74:75], v[182:183]
	v_pk_add_f32 v[80:81], v[72:73], v[180:181]
	v_pk_add_f32 v[78:79], v[94:95], v[228:229]
	v_pk_add_f32 v[76:77], v[92:93], v[226:227]
	v_pk_add_f32 v[74:75], v[86:87], v[232:233]
	v_pk_add_f32 v[72:73], v[84:85], v[230:231]
	v_pk_add_f32 v[70:71], v[70:71], v[236:237]
	v_pk_add_f32 v[68:69], v[68:69], v[234:235]
	v_pk_add_f32 v[66:67], v[66:67], v[240:241]
	v_pk_add_f32 v[64:65], v[64:65], v[238:239]
	v_lshl_add_u64 v[100:101], s[18:19], 0, v[100:101]
	v_lshlrev_b64 v[102:103], 13, v[200:201]
	v_lshl_add_u64 v[100:101], v[100:101], 0, v[214:215]
	v_lshl_add_u64 v[102:103], s[18:19], 0, v[102:103]
	global_load_dwordx4 v[144:147], v[100:101], off nt
	global_load_dwordx4 v[148:151], v[100:101], off offset:64 nt
	global_load_dwordx4 v[152:155], v[100:101], off offset:512 nt
	global_load_dwordx4 v[156:159], v[100:101], off offset:576 nt
	v_lshl_add_u64 v[100:101], v[102:103], 0, v[214:215]
	v_lshlrev_b64 v[102:103], 13, v[198:199]
	global_load_dwordx4 v[84:87], v[242:243], off nt
	global_load_dwordx4 v[92:95], v[242:243], off offset:64 nt
	global_load_dwordx4 v[168:171], v[100:101], off offset:512 nt
	global_load_dwordx4 v[180:183], v[100:101], off offset:576 nt
	v_lshl_add_u64 v[102:103], s[18:19], 0, v[102:103]
	global_load_dwordx4 v[160:163], v[100:101], off nt
	global_load_dwordx4 v[164:167], v[100:101], off offset:64 nt
	v_lshl_add_u64 v[100:101], v[102:103], 0, v[214:215]
	global_load_dwordx4 v[136:139], v[242:243], off offset:512 nt
	global_load_dwordx4 v[140:143], v[242:243], off offset:576 nt
	global_load_dwordx4 v[226:229], v[100:101], off nt
	global_load_dwordx4 v[230:233], v[100:101], off offset:64 nt
	global_load_dwordx4 v[234:237], v[100:101], off offset:512 nt
	global_load_dwordx4 v[238:241], v[100:101], off offset:576 nt
	v_lshlrev_b64 v[100:101], 11, v[212:213]
	v_lshl_add_u64 v[100:101], v[100:101], 0, v[196:197]
	v_lshl_add_u64 v[214:215], v[100:101], 2, s[12:13]
	v_lshl_add_u64 v[242:243], v[100:101], 1, s[22:23]
	v_mul_f32_e32 v100, v173, v173
	v_mul_f32_e32 v101, v175, v175
	v_mul_f32_e32 v102, v177, v177
	v_mul_f32_e32 v103, v179, v179
	v_mul_f32_e32 v108, v133, v133
	v_mul_f32_e32 v109, v135, v135
	v_fmac_f32_e32 v100, v172, v172
	v_fmac_f32_e32 v101, v174, v174
	v_fmac_f32_e32 v102, v176, v176
	v_fmac_f32_e32 v103, v178, v178
	v_fmac_f32_e32 v108, v132, v132
	v_fmac_f32_e32 v109, v134, v134
	v_add_f32_e32 v100, v100, v101
	v_add_f32_e32 v101, v102, v103
	v_add_f32_e32 v102, v108, v109
	v_add_f32_e32 v100, v100, v101
	v_add_f32_e32 v225, v102, v100
	v_cvt_pk_bf16_f32 v244, v172, v173
	v_cvt_pk_bf16_f32 v245, v174, v175
	v_cvt_pk_bf16_f32 v246, v176, v177
	v_cvt_pk_bf16_f32 v247, v178, v179
	s_waitcnt vmcnt(11)
; __device__ __forceinline__ unsigned cvt_pk_bf16(float lo, float hi) { f32x2_t f = {lo, hi}; bf16x2_t r = __builtin_convertvector(f, bf16x2_t); return __builtin_bit_cast(unsigned, r); }
;     __device__ __forceinline__ void operator()(f32x4 (&acc)[2][2][4][2], const Unit& u, int wr, int wc, int fr, int fq) const {
;     ...
;                     for (int n = 0; n < 2; ++n) acc[ai][bj][m][n] += *(const f32x4*)(base + off + bj * HALF + n * 16);
;                 if (m == 3) asm volatile("" : "+v"(acc[ai][0][0][0]), "+v"(acc[ai][0][0][1]), "+v"(acc[ai][1][0][0]), "+v"(acc[ai][1][0][1]), "+v"(acc[ai][0][1][0]), "+v"(acc[ai][0][1][1]), "+v"(acc[ai][1][1][0]), "+v"(acc[ai][1][1][1]),
;                                              "+v"(acc[ai][0][2][0]), "+v"(acc[ai][0][2][1]), "+v"(acc[ai][1][2][0]), "+v"(acc[ai][1][2][1]), "+v"(acc[ai][0][3][0]), "+v"(acc[ai][0][3][1]), "+v"(acc[ai][1][3][0]), "+v"(acc[ai][1][3][1]) :: "memory"); }
;         asm volatile("" ::: "memory");
; #pragma unroll
;         for (int ai = 0; ai < 2; ++ai)
; #pragma unroll
;             for (int m = 0; m < 4; ++m) { const int row = row0 + ai * HALF + m * 16; const size_t off = (size_t)row * ldc + col0; float sq = 0.f;
; #pragma unroll
;                 for (int bj = 0; bj < 2; ++bj)
; #pragma unroll
;                     for (int n = 0; n < 2; ++n) { const f32x4 v = acc[ai][bj][m][n]; *(f32x4*)(out + off + bj * HALF + n * 16) = v;
;                         if (xb) { u32x2e w; w.x = cvt_pk_bf16(v[0], v[1]); w.y = cvt_pk_bf16(v[2], v[3]); *(u32x2e*)(xb + off + bj * HALF + n * 16) = w; sq += (v[0] * v[0] + v[1] * v[1]) + (v[2] * v[2] + v[3] * v[3]); } }
;                 if (xb) { sq += __shfl_xor(sq, 16); sq += __shfl_xor(sq, 32); if (fq == 0) atomicAdd(ss + row, sq); } }
	v_pk_add_f32 v[110:111], v[62:63], v[86:87]
	s_waitcnt vmcnt(10)
	v_pk_add_f32 v[100:101], v[56:57], v[92:93]
	v_pk_add_f32 v[56:57], v[48:49], v[148:149]
	v_pk_add_f32 v[48:49], v[16:17], v[156:157]
	s_waitcnt vmcnt(8)
	v_pk_add_f32 v[16:17], v[8:9], v[180:181]
	v_pk_add_f32 v[102:103], v[58:59], v[94:95]
	v_pk_add_f32 v[58:59], v[50:51], v[150:151]
	v_pk_add_f32 v[50:51], v[18:19], v[158:159]
	s_waitcnt vmcnt(2)
	v_pk_add_f32 v[8:9], v[20:21], v[230:231]
	v_mul_f32_e32 v20, v129, v129
	v_mul_f32_e32 v21, v131, v131
	v_fmac_f32_e32 v20, v128, v128
	v_fmac_f32_e32 v21, v130, v130
	v_add_f32_e32 v20, v20, v21
	v_pk_add_f32 v[18:19], v[10:11], v[182:183]
	v_pk_add_f32 v[10:11], v[22:23], v[232:233]
	v_add_f32_e32 v22, v20, v225
	ds_bpermute_b32 v23, v222, v22
	v_pk_add_f32 v[108:109], v[60:61], v[84:85]
	v_pk_add_f32 v[94:95], v[42:43], v[138:139]
	v_pk_add_f32 v[92:93], v[40:41], v[136:137]
	v_pk_add_f32 v[86:87], v[34:35], v[142:143]
	v_pk_add_f32 v[84:85], v[32:33], v[140:141]
	v_pk_add_f32 v[62:63], v[54:55], v[146:147]
	v_pk_add_f32 v[60:61], v[52:53], v[144:145]
	v_pk_add_f32 v[54:55], v[26:27], v[154:155]
	v_pk_add_f32 v[52:53], v[24:25], v[152:153]
	v_pk_add_f32 v[42:43], v[46:47], v[162:163]
	v_pk_add_f32 v[40:41], v[44:45], v[160:161]
	v_pk_add_f32 v[34:35], v[38:39], v[166:167]
	v_pk_add_f32 v[32:33], v[36:37], v[164:165]
	v_pk_add_f32 v[26:27], v[14:15], v[170:171]
	v_pk_add_f32 v[24:25], v[12:13], v[168:169]
	v_pk_add_f32 v[14:15], v[30:31], v[228:229]
	v_pk_add_f32 v[12:13], v[28:29], v[226:227]
	s_waitcnt vmcnt(1)
	v_pk_add_f32 v[6:7], v[6:7], v[236:237]
	v_pk_add_f32 v[4:5], v[4:5], v[234:235]
	s_waitcnt vmcnt(0)
	v_pk_add_f32 v[2:3], v[2:3], v[240:241]
	v_pk_add_f32 v[0:1], v[0:1], v[238:239]
	v_cvt_pk_bf16_f32 v20, v132, v133
	v_cvt_pk_bf16_f32 v21, v134, v135
	global_store_dwordx4 v[214:215], v[172:175], off
	global_store_dwordx2 v[242:243], v[244:245], off
	global_store_dwordx4 v[214:215], v[176:179], off offset:64
	global_store_dwordx2 v[242:243], v[246:247], off offset:32
	global_store_dwordx4 v[214:215], v[132:135], off offset:512
	global_store_dwordx2 v[242:243], v[20:21], off offset:256
	s_waitcnt lgkmcnt(0)
	v_add_f32_e32 v20, v22, v23
	ds_bpermute_b32 v21, v221, v20
	v_cvt_pk_bf16_f32 v22, v128, v129
	v_cvt_pk_bf16_f32 v23, v130, v131
	global_store_dwordx4 v[214:215], v[128:131], off offset:576
	global_store_dwordx2 v[242:243], v[22:23], off offset:288
	s_and_saveexec_b64 s[38:39], s[8:9]
	s_cbranch_execz .LBB0_700
	v_lshl_add_u64 v[22:23], v[212:213], 2, s[14:15]
	s_waitcnt lgkmcnt(0)
	v_add_f32_e32 v20, v20, v21
	global_atomic_add_f32 v[22:23], v20, off

; __device__ __forceinline__ unsigned cvt_pk_bf16(float lo, float hi) { f32x2_t f = {lo, hi}; bf16x2_t r = __builtin_convertvector(f, bf16x2_t); return __builtin_bit_cast(unsigned, r); }
;     __device__ __forceinline__ void operator()(f32x4 (&acc)[2][2][4][2], const Unit& u, int wr, int wc, int fr, int fq) const {
;         const int row0 = u.pm * BM + wr * 64 + fr; const int col0 = u.pn * BM + wc * 32 + 4 * fq;
; #pragma unroll
;         for (int ai = 0; ai < 2; ++ai)
; #pragma unroll
;             for (int m = 0; m < 4; ++m) { const size_t off = (size_t)(row0 + ai * HALF + m * 16) * ldc + col0;
; #pragma unroll
;                 for (int bj = 0; bj < 2; ++bj)
; #pragma unroll
;                     for (int n = 0; n < 2; ++n) acc[ai][bj][m][n] += *(const f32x4*)(base + off + bj * HALF + n * 16);
;                 if (m == 3) asm volatile("" : "+v"(acc[ai][0][0][0]), "+v"(acc[ai][0][0][1]), "+v"(acc[ai][1][0][0]), "+v"(acc[ai][1][0][1]), "+v"(acc[ai][0][1][0]), "+v"(acc[ai][0][1][1]), "+v"(acc[ai][1][1][0]), "+v"(acc[ai][1][1][1]),
;                                              "+v"(acc[ai][0][2][0]), "+v"(acc[ai][0][2][1]), "+v"(acc[ai][1][2][0]), "+v"(acc[ai][1][2][1]), "+v"(acc[ai][0][3][0]), "+v"(acc[ai][0][3][1]), "+v"(acc[ai][1][3][0]), "+v"(acc[ai][1][3][1]) :: "memory"); }
;         asm volatile("" ::: "memory");
; #pragma unroll
;         for (int ai = 0; ai < 2; ++ai)
; #pragma unroll
;             for (int m = 0; m < 4; ++m) { const int row = row0 + ai * HALF + m * 16; const size_t off = (size_t)row * ldc + col0; float sq = 0.f;
; #pragma unroll
;                 for (int bj = 0; bj < 2; ++bj)
; #pragma unroll
;                     for (int n = 0; n < 2; ++n) { const f32x4 v = acc[ai][bj][m][n]; *(f32x4*)(out + off + bj * HALF + n * 16) = v;
;                         if (xb) { u32x2e w; w.x = cvt_pk_bf16(v[0], v[1]); w.y = cvt_pk_bf16(v[2], v[3]); *(u32x2e*)(xb + off + bj * HALF + n * 16) = w; sq += (v[0] * v[0] + v[1] * v[1]) + (v[2] * v[2] + v[3] * v[3]); } }
;                 if (xb) { sq += __shfl_xor(sq, 16); sq += __shfl_xor(sq, 32); if (fq == 0) atomicAdd(ss + row, sq); } }
.LBB0_1143:
	v_lshl_add_u32 v156, s66, 8, v176
	v_lshl_or_b32 v144, s67, 8, v178
	v_ashrrev_i32_e32 v157, 31, v156
	v_ashrrev_i32_e32 v145, 31, v144
	v_lshlrev_b64 v[128:129], 13, v[156:157]
	v_lshl_add_u64 v[128:129], s[20:21], 0, v[128:129]
	v_lshlrev_b64 v[170:171], 2, v[144:145]
	v_lshl_add_u64 v[172:173], v[128:129], 0, v[170:171]
	global_load_dwordx4 v[128:131], v[172:173], off nt
	v_or_b32_e32 v154, 16, v156
	v_ashrrev_i32_e32 v155, 31, v154
	v_or_b32_e32 v150, 32, v156
	v_ashrrev_i32_e32 v151, 31, v150
	v_or_b32_e32 v146, 48, v156
	v_ashrrev_i32_e32 v147, 31, v146
	v_lshlrev_b64 v[174:175], 11, v[156:157]
	v_lshl_add_u64 v[174:175], v[174:175], 0, v[144:145]
	v_lshl_add_u64 v[174:175], v[174:175], 1, s[24:25]
	s_waitcnt vmcnt(0)
	v_pk_add_f32 v[130:131], v[122:123], v[130:131]
	v_pk_add_f32 v[128:129], v[120:121], v[128:129]
	global_load_dwordx4 v[120:123], v[172:173], off offset:64 nt
	s_waitcnt vmcnt(0)
	v_pk_add_f32 v[122:123], v[118:119], v[122:123]
	v_pk_add_f32 v[120:121], v[116:117], v[120:121]
	global_load_dwordx4 v[116:119], v[172:173], off offset:512 nt
	s_waitcnt vmcnt(0)
	v_pk_add_f32 v[118:119], v[114:115], v[118:119]
	v_pk_add_f32 v[116:117], v[112:113], v[116:117]
	global_load_dwordx4 v[112:115], v[172:173], off offset:576 nt
	s_waitcnt vmcnt(0)
	v_pk_add_f32 v[112:113], v[96:97], v[112:113]
	v_lshlrev_b64 v[96:97], 13, v[154:155]
	v_lshl_add_u64 v[96:97], s[20:21], 0, v[96:97]
	v_lshl_add_u64 v[158:159], v[96:97], 0, v[170:171]
	v_pk_add_f32 v[114:115], v[98:99], v[114:115]
	global_load_dwordx4 v[96:99], v[158:159], off nt
	s_waitcnt vmcnt(0)
	v_pk_add_f32 v[98:99], v[102:103], v[98:99]
	v_pk_add_f32 v[96:97], v[100:101], v[96:97]
	global_load_dwordx4 v[100:103], v[158:159], off offset:64 nt
	s_waitcnt vmcnt(0)
	v_pk_add_f32 v[102:103], v[94:95], v[102:103]
	v_pk_add_f32 v[100:101], v[92:93], v[100:101]
	global_load_dwordx4 v[92:95], v[158:159], off offset:512 nt
	s_waitcnt vmcnt(0)
	v_pk_add_f32 v[82:83], v[82:83], v[94:95]
	v_pk_add_f32 v[80:81], v[80:81], v[92:93]
	global_load_dwordx4 v[92:95], v[158:159], off offset:576 nt
	s_waitcnt vmcnt(0)
	v_pk_add_f32 v[92:93], v[84:85], v[92:93]
	v_lshlrev_b64 v[84:85], 13, v[150:151]
	v_lshl_add_u64 v[84:85], s[20:21], 0, v[84:85]
	v_lshl_add_u64 v[152:153], v[84:85], 0, v[170:171]
	v_pk_add_f32 v[94:95], v[86:87], v[94:95]
	global_load_dwordx4 v[84:87], v[152:153], off nt
	s_waitcnt vmcnt(0)
	v_pk_add_f32 v[86:87], v[90:91], v[86:87]
	v_pk_add_f32 v[84:85], v[88:89], v[84:85]
	global_load_dwordx4 v[88:91], v[152:153], off offset:64 nt
	s_waitcnt vmcnt(0)
	v_pk_add_f32 v[90:91], v[62:63], v[90:91]
	v_pk_add_f32 v[88:89], v[60:61], v[88:89]
	global_load_dwordx4 v[60:63], v[152:153], off offset:512 nt
	s_waitcnt vmcnt(0)
	v_pk_add_f32 v[50:51], v[50:51], v[62:63]
	v_pk_add_f32 v[48:49], v[48:49], v[60:61]
	global_load_dwordx4 v[60:63], v[152:153], off offset:576 nt
	s_waitcnt vmcnt(0)
	v_pk_add_f32 v[60:61], v[52:53], v[60:61]
	v_lshlrev_b64 v[52:53], 13, v[146:147]
	v_lshl_add_u64 v[52:53], s[20:21], 0, v[52:53]
	v_lshl_add_u64 v[148:149], v[52:53], 0, v[170:171]
	v_pk_add_f32 v[62:63], v[54:55], v[62:63]
	global_load_dwordx4 v[52:55], v[148:149], off nt
	s_waitcnt vmcnt(0)
	v_pk_add_f32 v[54:55], v[126:127], v[54:55]
	v_pk_add_f32 v[52:53], v[124:125], v[52:53]
	global_load_dwordx4 v[124:127], v[148:149], off offset:64 nt
	s_waitcnt vmcnt(0)
	v_pk_add_f32 v[58:59], v[58:59], v[126:127]
	v_pk_add_f32 v[56:57], v[56:57], v[124:125]
	global_load_dwordx4 v[124:127], v[148:149], off offset:512 nt
	s_waitcnt vmcnt(0)
	v_pk_add_f32 v[42:43], v[42:43], v[126:127]
	v_pk_add_f32 v[40:41], v[40:41], v[124:125]
	global_load_dwordx4 v[124:127], v[148:149], off offset:576 nt
	s_waitcnt vmcnt(0)
	v_pk_add_f32 v[44:45], v[44:45], v[124:125]
	v_add_u32_e32 v124, 0x80, v156
	v_ashrrev_i32_e32 v125, 31, v124
	v_pk_add_f32 v[46:47], v[46:47], v[126:127]
	v_lshlrev_b64 v[126:127], 13, v[124:125]
	v_lshl_add_u64 v[126:127], s[20:21], 0, v[126:127]
	v_lshl_add_u64 v[164:165], v[126:127], 0, v[170:171]
	global_load_dwordx4 v[160:163], v[164:165], off nt
	v_add_u32_e32 v126, 0x90, v156
	v_ashrrev_i32_e32 v127, 31, v126
	s_waitcnt vmcnt(0)
	v_pk_add_f32 v[110:111], v[110:111], v[162:163]
	v_pk_add_f32 v[108:109], v[108:109], v[160:161]
	global_load_dwordx4 v[160:163], v[164:165], off offset:64 nt
	s_waitcnt vmcnt(0)
	v_pk_add_f32 v[106:107], v[106:107], v[162:163]
	v_pk_add_f32 v[104:105], v[104:105], v[160:161]
	global_load_dwordx4 v[160:163], v[164:165], off offset:512 nt
	s_waitcnt vmcnt(0)
	v_pk_add_f32 v[78:79], v[78:79], v[162:163]
	v_pk_add_f32 v[76:77], v[76:77], v[160:161]
	global_load_dwordx4 v[160:163], v[164:165], off offset:576 nt
	s_waitcnt vmcnt(0)
; __device__ __forceinline__ unsigned cvt_pk_bf16(float lo, float hi) { f32x2_t f = {lo, hi}; bf16x2_t r = __builtin_convertvector(f, bf16x2_t); return __builtin_bit_cast(unsigned, r); }
;     __device__ __forceinline__ void operator()(f32x4 (&acc)[2][2][4][2], const Unit& u, int wr, int wc, int fr, int fq) const {
;     ...
;                     for (int n = 0; n < 2; ++n) acc[ai][bj][m][n] += *(const f32x4*)(base + off + bj * HALF + n * 16);
;                 if (m == 3) asm volatile("" : "+v"(acc[ai][0][0][0]), "+v"(acc[ai][0][0][1]), "+v"(acc[ai][1][0][0]), "+v"(acc[ai][1][0][1]), "+v"(acc[ai][0][1][0]), "+v"(acc[ai][0][1][1]), "+v"(acc[ai][1][1][0]), "+v"(acc[ai][1][1][1]),
;                                              "+v"(acc[ai][0][2][0]), "+v"(acc[ai][0][2][1]), "+v"(acc[ai][1][2][0]), "+v"(acc[ai][1][2][1]), "+v"(acc[ai][0][3][0]), "+v"(acc[ai][0][3][1]), "+v"(acc[ai][1][3][0]), "+v"(acc[ai][1][3][1]) :: "memory"); }
;         asm volatile("" ::: "memory");
; #pragma unroll
;         for (int ai = 0; ai < 2; ++ai)
; #pragma unroll
;             for (int m = 0; m < 4; ++m) { const int row = row0 + ai * HALF + m * 16; const size_t off = (size_t)row * ldc + col0; float sq = 0.f;
; #pragma unroll
;                 for (int bj = 0; bj < 2; ++bj)
; #pragma unroll
;                     for (int n = 0; n < 2; ++n) { const f32x4 v = acc[ai][bj][m][n]; *(f32x4*)(out + off + bj * HALF + n * 16) = v;
;                         if (xb) { u32x2e w; w.x = cvt_pk_bf16(v[0], v[1]); w.y = cvt_pk_bf16(v[2], v[3]); *(u32x2e*)(xb + off + bj * HALF + n * 16) = w; sq += (v[0] * v[0] + v[1] * v[1]) + (v[2] * v[2] + v[3] * v[3]); } }
;                 if (xb) { sq += __shfl_xor(sq, 16); sq += __shfl_xor(sq, 32); if (fq == 0) atomicAdd(ss + row, sq); } }
	v_pk_add_f32 v[72:73], v[72:73], v[160:161]
	v_lshlrev_b64 v[160:161], 13, v[126:127]
	v_lshl_add_u64 v[160:161], s[20:21], 0, v[160:161]
	v_lshl_add_u64 v[166:167], v[160:161], 0, v[170:171]
	v_pk_add_f32 v[74:75], v[74:75], v[162:163]
	global_load_dwordx4 v[160:163], v[166:167], off nt
	s_waitcnt vmcnt(0)
	v_pk_add_f32 v[70:71], v[70:71], v[162:163]
	v_pk_add_f32 v[68:69], v[68:69], v[160:161]
	global_load_dwordx4 v[160:163], v[166:167], off offset:64 nt
	s_waitcnt vmcnt(0)
	v_pk_add_f32 v[66:67], v[66:67], v[162:163]
	v_pk_add_f32 v[64:65], v[64:65], v[160:161]
	global_load_dwordx4 v[160:163], v[166:167], off offset:512 nt
	s_waitcnt vmcnt(0)
	v_pk_add_f32 v[38:39], v[38:39], v[162:163]
	v_pk_add_f32 v[36:37], v[36:37], v[160:161]
	global_load_dwordx4 v[160:163], v[166:167], off offset:576 nt
	s_waitcnt vmcnt(0)
	v_pk_add_f32 v[32:33], v[32:33], v[160:161]
	v_add_u32_e32 v160, 0xa0, v156
	v_ashrrev_i32_e32 v161, 31, v160
	v_pk_add_f32 v[34:35], v[34:35], v[162:163]
	v_lshlrev_b64 v[162:163], 13, v[160:161]
	v_lshl_add_u64 v[162:163], s[20:21], 0, v[162:163]
	v_lshl_add_u64 v[168:169], v[162:163], 0, v[170:171]
	global_load_dwordx4 v[182:185], v[168:169], off nt
	v_add_u32_e32 v162, 0xb0, v156
	v_ashrrev_i32_e32 v163, 31, v162
	s_waitcnt vmcnt(0)
	v_pk_add_f32 v[30:31], v[30:31], v[184:185]
	v_pk_add_f32 v[28:29], v[28:29], v[182:183]
	global_load_dwordx4 v[182:185], v[168:169], off offset:64 nt
	s_waitcnt vmcnt(0)
	v_pk_add_f32 v[26:27], v[26:27], v[184:185]
	v_pk_add_f32 v[24:25], v[24:25], v[182:183]
	global_load_dwordx4 v[182:185], v[168:169], off offset:512 nt
	s_waitcnt vmcnt(0)
	v_pk_add_f32 v[22:23], v[22:23], v[184:185]
	v_pk_add_f32 v[20:21], v[20:21], v[182:183]
	global_load_dwordx4 v[182:185], v[168:169], off offset:576 nt
	s_waitcnt vmcnt(0)
	v_pk_add_f32 v[16:17], v[16:17], v[182:183]
	v_lshlrev_b64 v[182:183], 13, v[162:163]
	v_lshl_add_u64 v[182:183], s[20:21], 0, v[182:183]
	v_lshl_add_u64 v[170:171], v[182:183], 0, v[170:171]
	v_pk_add_f32 v[18:19], v[18:19], v[184:185]
	global_load_dwordx4 v[182:185], v[170:171], off nt
	s_waitcnt vmcnt(0)
	v_pk_add_f32 v[14:15], v[14:15], v[184:185]
	v_pk_add_f32 v[12:13], v[12:13], v[182:183]
	global_load_dwordx4 v[182:185], v[170:171], off offset:64 nt
	s_waitcnt vmcnt(0)
	v_pk_add_f32 v[10:11], v[10:11], v[184:185]
	v_pk_add_f32 v[8:9], v[8:9], v[182:183]
	global_load_dwordx4 v[182:185], v[170:171], off offset:512 nt
	s_waitcnt vmcnt(0)
	v_pk_add_f32 v[6:7], v[6:7], v[184:185]
	v_pk_add_f32 v[4:5], v[4:5], v[182:183]
	global_load_dwordx4 v[182:185], v[170:171], off offset:576 nt
	s_waitcnt vmcnt(0)
	v_pk_add_f32 v[2:3], v[2:3], v[184:185]
	v_pk_add_f32 v[0:1], v[0:1], v[182:183]
	v_cvt_pk_bf16_f32 v182, v128, v129
	global_store_dwordx4 v[172:173], v[128:131], off
	v_cvt_pk_bf16_f32 v183, v130, v131
	global_store_dwordx2 v[174:175], v[182:183], off
	v_mul_f32_e32 v129, v129, v129
	v_fmac_f32_e32 v129, v128, v128
	v_mul_f32_e32 v128, v131, v131
	v_fmac_f32_e32 v128, v130, v130
	v_add_f32_e32 v130, v129, v128
	global_store_dwordx4 v[172:173], v[120:123], off offset:64
	v_cvt_pk_bf16_f32 v128, v120, v121
	v_cvt_pk_bf16_f32 v129, v122, v123
	v_mul_f32_e32 v121, v121, v121
	v_fmac_f32_e32 v121, v120, v120
	v_mul_f32_e32 v120, v123, v123
	v_fmac_f32_e32 v120, v122, v122
	v_add_f32_e32 v120, v121, v120
	global_store_dwordx2 v[174:175], v[128:129], off offset:32
	v_add_f32_e32 v122, v130, v120
	global_store_dwordx4 v[172:173], v[116:119], off offset:512
	v_cvt_pk_bf16_f32 v120, v116, v117
	v_cvt_pk_bf16_f32 v121, v118, v119
	v_mul_f32_e32 v117, v117, v117
	v_fmac_f32_e32 v117, v116, v116
	v_mul_f32_e32 v116, v119, v119
	v_fmac_f32_e32 v116, v118, v118
	v_add_f32_e32 v116, v117, v116
	global_store_dwordx2 v[174:175], v[120:121], off offset:256
	v_add_f32_e32 v118, v116, v122
	global_store_dwordx4 v[172:173], v[112:115], off offset:576
	v_cvt_pk_bf16_f32 v116, v112, v113
	v_cvt_pk_bf16_f32 v117, v114, v115
	v_mul_f32_e32 v113, v113, v113
	v_fmac_f32_e32 v113, v112, v112
	v_mul_f32_e32 v112, v115, v115
	v_fmac_f32_e32 v112, v114, v114
	v_add_f32_e32 v112, v113, v112
	v_add_f32_e32 v112, v112, v118
	ds_bpermute_b32 v113, v222, v112
	global_store_dwordx2 v[174:175], v[116:117], off offset:288
	s_waitcnt lgkmcnt(0)
	v_add_f32_e32 v112, v112, v113
	ds_bpermute_b32 v113, v221, v112
	s_and_saveexec_b64 s[34:35], s[10:11]
	s_cbranch_execz .LBB0_1145
	v_lshl_add_u64 v[114:115], v[156:157], 2, s[22:23]
	s_waitcnt lgkmcnt(0)
	v_add_f32_e32 v112, v112, v113
	global_atomic_add_f32 v[114:115], v112, off

; __device__ __forceinline__ unsigned cvt_pk_bf16(float lo, float hi) { f32x2_t f = {lo, hi}; bf16x2_t r = __builtin_convertvector(f, bf16x2_t); return __builtin_bit_cast(unsigned, r); }
;     __device__ __forceinline__ void operator()(f32x4 (&acc)[2][2][4][2], const Unit& u, int wr, int wc, int fr, int fq) const {
;         const int row0 = u.pm * BM + wr * 64 + fr; const int col0 = u.pn * BM + wc * 32 + 4 * fq;
; #pragma unroll
;         for (int ai = 0; ai < 2; ++ai)
; #pragma unroll
;             for (int m = 0; m < 4; ++m) { const size_t off = (size_t)(row0 + ai * HALF + m * 16) * ldc + col0;
; #pragma unroll
;                 for (int bj = 0; bj < 2; ++bj)
; #pragma unroll
;                     for (int n = 0; n < 2; ++n) acc[ai][bj][m][n] += *(const f32x4*)(base + off + bj * HALF + n * 16);
;                 if (m == 3) asm volatile("" : "+v"(acc[ai][0][0][0]), "+v"(acc[ai][0][0][1]), "+v"(acc[ai][1][0][0]), "+v"(acc[ai][1][0][1]), "+v"(acc[ai][0][1][0]), "+v"(acc[ai][0][1][1]), "+v"(acc[ai][1][1][0]), "+v"(acc[ai][1][1][1]),
;                                              "+v"(acc[ai][0][2][0]), "+v"(acc[ai][0][2][1]), "+v"(acc[ai][1][2][0]), "+v"(acc[ai][1][2][1]), "+v"(acc[ai][0][3][0]), "+v"(acc[ai][0][3][1]), "+v"(acc[ai][1][3][0]), "+v"(acc[ai][1][3][1]) :: "memory"); }
;         asm volatile("" ::: "memory");
; #pragma unroll
;         for (int ai = 0; ai < 2; ++ai)
; #pragma unroll
;             for (int m = 0; m < 4; ++m) { const int row = row0 + ai * HALF + m * 16; const size_t off = (size_t)row * ldc + col0; float sq = 0.f;
; #pragma unroll
;                 for (int bj = 0; bj < 2; ++bj)
; #pragma unroll
;                     for (int n = 0; n < 2; ++n) { const f32x4 v = acc[ai][bj][m][n]; *(f32x4*)(out + off + bj * HALF + n * 16) = v;
;                         if (xb) { u32x2e w; w.x = cvt_pk_bf16(v[0], v[1]); w.y = cvt_pk_bf16(v[2], v[3]); *(u32x2e*)(xb + off + bj * HALF + n * 16) = w; sq += (v[0] * v[0] + v[1] * v[1]) + (v[2] * v[2] + v[3] * v[3]); } }
;                 if (xb) { sq += __shfl_xor(sq, 16); sq += __shfl_xor(sq, 32); if (fq == 0) atomicAdd(ss + row, sq); } }
.LBB0_1479:
	v_lshl_add_u32 v156, s36, 8, v176
	v_lshl_or_b32 v144, s38, 8, v178
	v_ashrrev_i32_e32 v157, 31, v156
	v_ashrrev_i32_e32 v145, 31, v144
	v_lshlrev_b64 v[128:129], 13, v[156:157]
	v_lshl_add_u64 v[128:129], s[12:13], 0, v[128:129]
	v_lshlrev_b64 v[170:171], 2, v[144:145]
	v_lshl_add_u64 v[172:173], v[128:129], 0, v[170:171]
	global_load_dwordx4 v[128:131], v[172:173], off nt
	v_or_b32_e32 v154, 16, v156
	v_ashrrev_i32_e32 v155, 31, v154
	v_or_b32_e32 v150, 32, v156
	v_ashrrev_i32_e32 v151, 31, v150
	v_or_b32_e32 v146, 48, v156
	v_ashrrev_i32_e32 v147, 31, v146
	v_lshlrev_b64 v[174:175], 11, v[156:157]
	v_lshl_add_u64 v[174:175], v[174:175], 0, v[144:145]
	v_lshl_add_u64 v[174:175], v[174:175], 1, s[20:21]
	s_waitcnt vmcnt(0)
	v_pk_add_f32 v[130:131], v[122:123], v[130:131]
	v_pk_add_f32 v[128:129], v[120:121], v[128:129]
	global_load_dwordx4 v[120:123], v[172:173], off offset:64 nt
	s_waitcnt vmcnt(0)
	v_pk_add_f32 v[122:123], v[118:119], v[122:123]
	v_pk_add_f32 v[120:121], v[116:117], v[120:121]
	global_load_dwordx4 v[116:119], v[172:173], off offset:512 nt
	s_waitcnt vmcnt(0)
	v_pk_add_f32 v[118:119], v[114:115], v[118:119]
	v_pk_add_f32 v[116:117], v[112:113], v[116:117]
	global_load_dwordx4 v[112:115], v[172:173], off offset:576 nt
	s_waitcnt vmcnt(0)
	v_pk_add_f32 v[112:113], v[96:97], v[112:113]
	v_lshlrev_b64 v[96:97], 13, v[154:155]
	v_lshl_add_u64 v[96:97], s[12:13], 0, v[96:97]
	v_lshl_add_u64 v[158:159], v[96:97], 0, v[170:171]
	v_pk_add_f32 v[114:115], v[98:99], v[114:115]
	global_load_dwordx4 v[96:99], v[158:159], off nt
	s_waitcnt vmcnt(0)
	v_pk_add_f32 v[98:99], v[102:103], v[98:99]
	v_pk_add_f32 v[96:97], v[100:101], v[96:97]
	global_load_dwordx4 v[100:103], v[158:159], off offset:64 nt
	s_waitcnt vmcnt(0)
	v_pk_add_f32 v[102:103], v[94:95], v[102:103]
	v_pk_add_f32 v[100:101], v[92:93], v[100:101]
	global_load_dwordx4 v[92:95], v[158:159], off offset:512 nt
	s_waitcnt vmcnt(0)
	v_pk_add_f32 v[82:83], v[82:83], v[94:95]
	v_pk_add_f32 v[80:81], v[80:81], v[92:93]
	global_load_dwordx4 v[92:95], v[158:159], off offset:576 nt
	s_waitcnt vmcnt(0)
	v_pk_add_f32 v[92:93], v[84:85], v[92:93]
	v_lshlrev_b64 v[84:85], 13, v[150:151]
	v_lshl_add_u64 v[84:85], s[12:13], 0, v[84:85]
	v_lshl_add_u64 v[152:153], v[84:85], 0, v[170:171]
	v_pk_add_f32 v[94:95], v[86:87], v[94:95]
	global_load_dwordx4 v[84:87], v[152:153], off nt
	s_waitcnt vmcnt(0)
	v_pk_add_f32 v[86:87], v[90:91], v[86:87]
	v_pk_add_f32 v[84:85], v[88:89], v[84:85]
	global_load_dwordx4 v[88:91], v[152:153], off offset:64 nt
	s_waitcnt vmcnt(0)
	v_pk_add_f32 v[90:91], v[62:63], v[90:91]
	v_pk_add_f32 v[88:89], v[60:61], v[88:89]
	global_load_dwordx4 v[60:63], v[152:153], off offset:512 nt
	s_waitcnt vmcnt(0)
	v_pk_add_f32 v[50:51], v[50:51], v[62:63]
	v_pk_add_f32 v[48:49], v[48:49], v[60:61]
	global_load_dwordx4 v[60:63], v[152:153], off offset:576 nt
	s_waitcnt vmcnt(0)
	v_pk_add_f32 v[60:61], v[52:53], v[60:61]
	v_lshlrev_b64 v[52:53], 13, v[146:147]
	v_lshl_add_u64 v[52:53], s[12:13], 0, v[52:53]
	v_lshl_add_u64 v[148:149], v[52:53], 0, v[170:171]
	v_pk_add_f32 v[62:63], v[54:55], v[62:63]
	global_load_dwordx4 v[52:55], v[148:149], off nt
	s_waitcnt vmcnt(0)
	v_pk_add_f32 v[54:55], v[126:127], v[54:55]
	v_pk_add_f32 v[52:53], v[124:125], v[52:53]
	global_load_dwordx4 v[124:127], v[148:149], off offset:64 nt
	s_waitcnt vmcnt(0)
	v_pk_add_f32 v[58:59], v[58:59], v[126:127]
	v_pk_add_f32 v[56:57], v[56:57], v[124:125]
	global_load_dwordx4 v[124:127], v[148:149], off offset:512 nt
	s_waitcnt vmcnt(0)
	v_pk_add_f32 v[42:43], v[42:43], v[126:127]
	v_pk_add_f32 v[40:41], v[40:41], v[124:125]
	global_load_dwordx4 v[124:127], v[148:149], off offset:576 nt
	s_waitcnt vmcnt(0)
	v_pk_add_f32 v[44:45], v[44:45], v[124:125]
	v_add_u32_e32 v124, 0x80, v156
	v_ashrrev_i32_e32 v125, 31, v124
	v_pk_add_f32 v[46:47], v[46:47], v[126:127]
	v_lshlrev_b64 v[126:127], 13, v[124:125]
	v_lshl_add_u64 v[126:127], s[12:13], 0, v[126:127]
	v_lshl_add_u64 v[164:165], v[126:127], 0, v[170:171]
	global_load_dwordx4 v[160:163], v[164:165], off nt
	v_add_u32_e32 v126, 0x90, v156
	v_ashrrev_i32_e32 v127, 31, v126
	s_waitcnt vmcnt(0)
	v_pk_add_f32 v[110:111], v[110:111], v[162:163]
	v_pk_add_f32 v[108:109], v[108:109], v[160:161]
	global_load_dwordx4 v[160:163], v[164:165], off offset:64 nt
	s_waitcnt vmcnt(0)
	v_pk_add_f32 v[106:107], v[106:107], v[162:163]
	v_pk_add_f32 v[104:105], v[104:105], v[160:161]
	global_load_dwordx4 v[160:163], v[164:165], off offset:512 nt
	s_waitcnt vmcnt(0)
; __device__ __forceinline__ unsigned cvt_pk_bf16(float lo, float hi) { f32x2_t f = {lo, hi}; bf16x2_t r = __builtin_convertvector(f, bf16x2_t); return __builtin_bit_cast(unsigned, r); }
;     __device__ __forceinline__ void operator()(f32x4 (&acc)[2][2][4][2], const Unit& u, int wr, int wc, int fr, int fq) const {
;     ...
;                     for (int n = 0; n < 2; ++n) acc[ai][bj][m][n] += *(const f32x4*)(base + off + bj * HALF + n * 16);
;                 if (m == 3) asm volatile("" : "+v"(acc[ai][0][0][0]), "+v"(acc[ai][0][0][1]), "+v"(acc[ai][1][0][0]), "+v"(acc[ai][1][0][1]), "+v"(acc[ai][0][1][0]), "+v"(acc[ai][0][1][1]), "+v"(acc[ai][1][1][0]), "+v"(acc[ai][1][1][1]),
;                                              "+v"(acc[ai][0][2][0]), "+v"(acc[ai][0][2][1]), "+v"(acc[ai][1][2][0]), "+v"(acc[ai][1][2][1]), "+v"(acc[ai][0][3][0]), "+v"(acc[ai][0][3][1]), "+v"(acc[ai][1][3][0]), "+v"(acc[ai][1][3][1]) :: "memory"); }
;         asm volatile("" ::: "memory");
; #pragma unroll
;         for (int ai = 0; ai < 2; ++ai)
; #pragma unroll
;             for (int m = 0; m < 4; ++m) { const int row = row0 + ai * HALF + m * 16; const size_t off = (size_t)row * ldc + col0; float sq = 0.f;
; #pragma unroll
;                 for (int bj = 0; bj < 2; ++bj)
; #pragma unroll
;                     for (int n = 0; n < 2; ++n) { const f32x4 v = acc[ai][bj][m][n]; *(f32x4*)(out + off + bj * HALF + n * 16) = v;
;                         if (xb) { u32x2e w; w.x = cvt_pk_bf16(v[0], v[1]); w.y = cvt_pk_bf16(v[2], v[3]); *(u32x2e*)(xb + off + bj * HALF + n * 16) = w; sq += (v[0] * v[0] + v[1] * v[1]) + (v[2] * v[2] + v[3] * v[3]); } }
;                 if (xb) { sq += __shfl_xor(sq, 16); sq += __shfl_xor(sq, 32); if (fq == 0) atomicAdd(ss + row, sq); } }
	v_pk_add_f32 v[78:79], v[78:79], v[162:163]
	v_pk_add_f32 v[76:77], v[76:77], v[160:161]
	global_load_dwordx4 v[160:163], v[164:165], off offset:576 nt
	s_waitcnt vmcnt(0)
	v_pk_add_f32 v[72:73], v[72:73], v[160:161]
	v_lshlrev_b64 v[160:161], 13, v[126:127]
	v_lshl_add_u64 v[160:161], s[12:13], 0, v[160:161]
	v_lshl_add_u64 v[166:167], v[160:161], 0, v[170:171]
	v_pk_add_f32 v[74:75], v[74:75], v[162:163]
	global_load_dwordx4 v[160:163], v[166:167], off nt
	s_waitcnt vmcnt(0)
	v_pk_add_f32 v[70:71], v[70:71], v[162:163]
	v_pk_add_f32 v[68:69], v[68:69], v[160:161]
	global_load_dwordx4 v[160:163], v[166:167], off offset:64 nt
	s_waitcnt vmcnt(0)
	v_pk_add_f32 v[66:67], v[66:67], v[162:163]
	v_pk_add_f32 v[64:65], v[64:65], v[160:161]
	global_load_dwordx4 v[160:163], v[166:167], off offset:512 nt
	s_waitcnt vmcnt(0)
	v_pk_add_f32 v[38:39], v[38:39], v[162:163]
	v_pk_add_f32 v[36:37], v[36:37], v[160:161]
	global_load_dwordx4 v[160:163], v[166:167], off offset:576 nt
	s_waitcnt vmcnt(0)
	v_pk_add_f32 v[32:33], v[32:33], v[160:161]
	v_add_u32_e32 v160, 0xa0, v156
	v_ashrrev_i32_e32 v161, 31, v160
	v_pk_add_f32 v[34:35], v[34:35], v[162:163]
	v_lshlrev_b64 v[162:163], 13, v[160:161]
	v_lshl_add_u64 v[162:163], s[12:13], 0, v[162:163]
	v_lshl_add_u64 v[168:169], v[162:163], 0, v[170:171]
	global_load_dwordx4 v[182:185], v[168:169], off nt
	v_add_u32_e32 v162, 0xb0, v156
	v_ashrrev_i32_e32 v163, 31, v162
	s_waitcnt vmcnt(0)
	v_pk_add_f32 v[30:31], v[30:31], v[184:185]
	v_pk_add_f32 v[28:29], v[28:29], v[182:183]
	global_load_dwordx4 v[182:185], v[168:169], off offset:64 nt
	s_waitcnt vmcnt(0)
	v_pk_add_f32 v[26:27], v[26:27], v[184:185]
	v_pk_add_f32 v[24:25], v[24:25], v[182:183]
	global_load_dwordx4 v[182:185], v[168:169], off offset:512 nt
	s_waitcnt vmcnt(0)
	v_pk_add_f32 v[22:23], v[22:23], v[184:185]
	v_pk_add_f32 v[20:21], v[20:21], v[182:183]
	global_load_dwordx4 v[182:185], v[168:169], off offset:576 nt
	s_waitcnt vmcnt(0)
	v_pk_add_f32 v[16:17], v[16:17], v[182:183]
	v_lshlrev_b64 v[182:183], 13, v[162:163]
	v_lshl_add_u64 v[182:183], s[12:13], 0, v[182:183]
	v_lshl_add_u64 v[170:171], v[182:183], 0, v[170:171]
	v_pk_add_f32 v[18:19], v[18:19], v[184:185]
	global_load_dwordx4 v[182:185], v[170:171], off nt
	s_waitcnt vmcnt(0)
	v_pk_add_f32 v[14:15], v[14:15], v[184:185]
	v_pk_add_f32 v[12:13], v[12:13], v[182:183]
	global_load_dwordx4 v[182:185], v[170:171], off offset:64 nt
	s_waitcnt vmcnt(0)
	v_pk_add_f32 v[10:11], v[10:11], v[184:185]
	v_pk_add_f32 v[8:9], v[8:9], v[182:183]
	global_load_dwordx4 v[182:185], v[170:171], off offset:512 nt
	s_waitcnt vmcnt(0)
	v_pk_add_f32 v[6:7], v[6:7], v[184:185]
	v_pk_add_f32 v[4:5], v[4:5], v[182:183]
	global_load_dwordx4 v[182:185], v[170:171], off offset:576 nt
	s_waitcnt vmcnt(0)
	v_pk_add_f32 v[2:3], v[2:3], v[184:185]
	v_pk_add_f32 v[0:1], v[0:1], v[182:183]
	v_cvt_pk_bf16_f32 v182, v128, v129
	global_store_dwordx4 v[172:173], v[128:131], off
	v_cvt_pk_bf16_f32 v183, v130, v131
	global_store_dwordx2 v[174:175], v[182:183], off
	v_mul_f32_e32 v129, v129, v129
	v_fmac_f32_e32 v129, v128, v128
	v_mul_f32_e32 v128, v131, v131
	v_fmac_f32_e32 v128, v130, v130
	v_add_f32_e32 v130, v129, v128
	global_store_dwordx4 v[172:173], v[120:123], off offset:64
	v_cvt_pk_bf16_f32 v128, v120, v121
	v_cvt_pk_bf16_f32 v129, v122, v123
	v_mul_f32_e32 v121, v121, v121
	v_fmac_f32_e32 v121, v120, v120
	v_mul_f32_e32 v120, v123, v123
	v_fmac_f32_e32 v120, v122, v122
	v_add_f32_e32 v120, v121, v120
	global_store_dwordx2 v[174:175], v[128:129], off offset:32
	v_add_f32_e32 v122, v130, v120
	global_store_dwordx4 v[172:173], v[116:119], off offset:512
	v_cvt_pk_bf16_f32 v120, v116, v117
	v_cvt_pk_bf16_f32 v121, v118, v119
	v_mul_f32_e32 v117, v117, v117
	v_fmac_f32_e32 v117, v116, v116
	v_mul_f32_e32 v116, v119, v119
	v_fmac_f32_e32 v116, v118, v118
	v_add_f32_e32 v116, v117, v116
	global_store_dwordx2 v[174:175], v[120:121], off offset:256
	v_add_f32_e32 v118, v116, v122
	global_store_dwordx4 v[172:173], v[112:115], off offset:576
	v_cvt_pk_bf16_f32 v116, v112, v113
	v_cvt_pk_bf16_f32 v117, v114, v115
	v_mul_f32_e32 v113, v113, v113
	v_fmac_f32_e32 v113, v112, v112
	v_mul_f32_e32 v112, v115, v115
	v_fmac_f32_e32 v112, v114, v114
	v_add_f32_e32 v112, v113, v112
	v_add_f32_e32 v112, v112, v118
	ds_bpermute_b32 v113, v222, v112
	global_store_dwordx2 v[174:175], v[116:117], off offset:288
	s_waitcnt lgkmcnt(0)
	v_add_f32_e32 v112, v112, v113
	ds_bpermute_b32 v113, v221, v112
	s_and_saveexec_b64 s[36:37], s[6:7]
	s_cbranch_execz .LBB0_1481
	v_lshl_add_u64 v[114:115], v[156:157], 2, s[14:15]
	s_waitcnt lgkmcnt(0)
	v_add_f32_e32 v112, v112, v113
	global_atomic_add_f32 v[114:115], v112, off

;     __device__ __forceinline__ void operator()(f32x4 (&acc)[2][2][4][2], const Unit& u, int wr, int wc, int fr, int fq) const {
;         const int row0 = u.pm * BM + wr * 64 + fr; const int col0 = u.pn * BM + wc * 32 + 4 * fq;
; #pragma unroll
;         for (int ai = 0; ai < 2; ++ai)
; #pragma unroll
;             for (int m = 0; m < 4; ++m) { const size_t off = (size_t)(row0 + ai * HALF + m * 16) * ldc + col0;
; #pragma unroll
;                 for (int bj = 0; bj < 2; ++bj)
; #pragma unroll
;                     for (int n = 0; n < 2; ++n) acc[ai][bj][m][n] += *(const f32x4*)(base + off + bj * HALF + n * 16);
;                 if (m == 3) asm volatile("" : "+v"(acc[ai][0][0][0]), "+v"(acc[ai][0][0][1]), "+v"(acc[ai][1][0][0]), "+v"(acc[ai][1][0][1]), "+v"(acc[ai][0][1][0]), "+v"(acc[ai][0][1][1]), "+v"(acc[ai][1][1][0]), "+v"(acc[ai][1][1][1]),
;                                              "+v"(acc[ai][0][2][0]), "+v"(acc[ai][0][2][1]), "+v"(acc[ai][1][2][0]), "+v"(acc[ai][1][2][1]), "+v"(acc[ai][0][3][0]), "+v"(acc[ai][0][3][1]), "+v"(acc[ai][1][3][0]), "+v"(acc[ai][1][3][1]) :: "memory"); }
;         asm volatile("" ::: "memory");
; #pragma unroll
;         for (int ai = 0; ai < 2; ++ai)
; #pragma unroll
;             for (int m = 0; m < 4; ++m) { const int row = row0 + ai * HALF + m * 16; const size_t off = (size_t)row * ldc + col0; float sq = 0.f;
; #pragma unroll
;                 for (int bj = 0; bj < 2; ++bj)
; #pragma unroll
;                     for (int n = 0; n < 2; ++n) { const f32x4 v = acc[ai][bj][m][n]; *(f32x4*)(out + off + bj * HALF + n * 16) = v;
.LBB0_1902:
	v_lshl_add_u32 v146, s54, 8, v154
	v_lshl_or_b32 v140, s55, 8, v156
	v_ashrrev_i32_e32 v147, 31, v146
	v_ashrrev_i32_e32 v141, 31, v140
	v_lshlrev_b64 v[142:143], 13, v[146:147]
	v_lshl_add_u64 v[142:143], s[8:9], 0, v[142:143]
	v_lshlrev_b64 v[148:149], 2, v[140:141]
	v_lshl_add_u64 v[140:141], v[142:143], 0, v[148:149]
	v_or_b32_e32 v142, 16, v146
	v_or_b32_e32 v144, 32, v146
	v_or_b32_e32 v146, 48, v146
	v_ashrrev_i32_e32 v143, 31, v142
	v_ashrrev_i32_e32 v145, 31, v144
	v_ashrrev_i32_e32 v147, 31, v146
	v_lshlrev_b64 v[142:143], 13, v[142:143]
	v_lshlrev_b64 v[144:145], 13, v[144:145]
	v_lshlrev_b64 v[146:147], 13, v[146:147]
	v_lshl_add_u64 v[142:143], s[8:9], 0, v[142:143]
	v_lshl_add_u64 v[144:145], s[8:9], 0, v[144:145]
	v_lshl_add_u64 v[146:147], s[8:9], 0, v[146:147]
	v_lshl_add_u64 v[142:143], v[142:143], 0, v[148:149]
	v_lshl_add_u64 v[144:145], v[144:145], 0, v[148:149]
	v_lshl_add_u64 v[146:147], v[146:147], 0, v[148:149]
	global_load_dwordx4 v[160:163], v[140:141], off nt
	global_load_dwordx4 v[164:167], v[140:141], off offset:64 nt
	global_load_dwordx4 v[168:171], v[140:141], off offset:512 nt
	global_load_dwordx4 v[172:175], v[140:141], off offset:576 nt
	global_load_dwordx4 v[176:179], v[142:143], off nt
	global_load_dwordx4 v[180:183], v[142:143], off offset:64 nt
	global_load_dwordx4 v[184:187], v[142:143], off offset:512 nt
	global_load_dwordx4 v[188:191], v[142:143], off offset:576 nt
	global_load_dwordx4 v[192:195], v[144:145], off nt
	global_load_dwordx4 v[196:199], v[144:145], off offset:64 nt
	global_load_dwordx4 v[200:203], v[144:145], off offset:512 nt
	global_load_dwordx4 v[204:207], v[144:145], off offset:576 nt
	global_load_dwordx4 v[208:211], v[146:147], off nt
	global_load_dwordx4 v[212:215], v[146:147], off offset:64 nt
	global_load_dwordx4 v[216:219], v[146:147], off offset:512 nt
	global_load_dwordx4 v[220:223], v[146:147], off offset:576 nt
	v_add_co_u32_e32 v150, vcc, s48, v140
	v_lshl_add_u64 v[148:149], v[140:141], 0, s[16:17]
	s_nop 0
	v_addc_co_u32_e32 v151, vcc, 0, v141, vcc
	v_add_co_u32_e32 v224, vcc, s49, v140
	v_lshl_add_u64 v[232:233], v[140:141], 0, s[6:7]
	s_nop 0
	v_addc_co_u32_e32 v225, vcc, 0, v141, vcc
	v_add_co_u32_e32 v228, vcc, s50, v140
	v_lshl_add_u64 v[152:153], v[140:141], 0, s[18:19]
	s_nop 0
	v_addc_co_u32_e32 v229, vcc, 0, v141, vcc
	v_add_co_u32_e32 v230, vcc, s51, v140
	v_lshl_add_u64 v[226:227], v[140:141], 0, s[20:21]
	s_nop 0
	v_addc_co_u32_e32 v231, vcc, 0, v141, vcc
	s_and_b64 vcc, exec, s[0:1]
	s_mov_b64 s[0:1], -1
	s_waitcnt vmcnt(0)
	v_pk_add_f32 v[126:127], v[126:127], v[162:163]
	v_pk_add_f32 v[124:125], v[124:125], v[160:161]
	v_pk_add_f32 v[122:123], v[122:123], v[166:167]
	v_pk_add_f32 v[120:121], v[120:121], v[164:165]
	v_pk_add_f32 v[106:107], v[106:107], v[170:171]
	v_pk_add_f32 v[104:105], v[104:105], v[168:169]
	v_pk_add_f32 v[98:99], v[98:99], v[174:175]
	v_pk_add_f32 v[96:97], v[96:97], v[172:173]
	v_pk_add_f32 v[118:119], v[118:119], v[178:179]
	v_pk_add_f32 v[116:117], v[116:117], v[176:177]
	v_pk_add_f32 v[114:115], v[114:115], v[182:183]
	v_pk_add_f32 v[112:113], v[112:113], v[180:181]
	v_pk_add_f32 v[90:91], v[90:91], v[186:187]
	v_pk_add_f32 v[88:89], v[88:89], v[184:185]
	v_pk_add_f32 v[82:83], v[82:83], v[190:191]
	v_pk_add_f32 v[80:81], v[80:81], v[188:189]
	v_pk_add_f32 v[110:111], v[110:111], v[194:195]
	v_pk_add_f32 v[108:109], v[108:109], v[192:193]
	v_pk_add_f32 v[102:103], v[102:103], v[198:199]
	v_pk_add_f32 v[100:101], v[100:101], v[196:197]
	v_pk_add_f32 v[78:79], v[78:79], v[202:203]
	v_pk_add_f32 v[76:77], v[76:77], v[200:201]
	v_pk_add_f32 v[74:75], v[74:75], v[206:207]
	v_pk_add_f32 v[72:73], v[72:73], v[204:205]
	v_pk_add_f32 v[94:95], v[94:95], v[210:211]
	v_pk_add_f32 v[92:93], v[92:93], v[208:209]
	v_pk_add_f32 v[86:87], v[86:87], v[214:215]
	v_pk_add_f32 v[84:85], v[84:85], v[212:213]
	v_pk_add_f32 v[70:71], v[70:71], v[218:219]
	v_pk_add_f32 v[68:69], v[68:69], v[216:217]
	v_pk_add_f32 v[66:67], v[66:67], v[222:223]
	v_pk_add_f32 v[64:65], v[64:65], v[220:221]
	s_nop 0
	global_load_dwordx4 v[160:163], v[150:151], off nt
	global_load_dwordx4 v[164:167], v[148:149], off offset:64 nt
	global_load_dwordx4 v[168:171], v[148:149], off offset:512 nt
	global_load_dwordx4 v[172:175], v[148:149], off offset:576 nt
	global_load_dwordx4 v[176:179], v[224:225], off nt
	global_load_dwordx4 v[180:183], v[152:153], off offset:64 nt
	global_load_dwordx4 v[184:187], v[152:153], off offset:512 nt
	global_load_dwordx4 v[188:191], v[152:153], off offset:576 nt
	global_load_dwordx4 v[192:195], v[228:229], off nt
	global_load_dwordx4 v[196:199], v[226:227], off offset:64 nt
	global_load_dwordx4 v[200:203], v[226:227], off offset:512 nt
	global_load_dwordx4 v[204:207], v[226:227], off offset:576 nt
	global_load_dwordx4 v[208:211], v[230:231], off nt
	global_load_dwordx4 v[212:215], v[232:233], off offset:64 nt
	global_load_dwordx4 v[216:219], v[232:233], off offset:512 nt
	global_load_dwordx4 v[220:223], v[232:233], off offset:576 nt
	s_waitcnt vmcnt(15)
; #define PG8_BAR __builtin_amdgcn_s_barrier()
;     __device__ __forceinline__ void operator()(f32x4 (&acc)[2][2][4][2], const Unit& u, int wr, int wc, int fr, int fq) const {
;     ...
;                     for (int n = 0; n < 2; ++n) acc[ai][bj][m][n] += *(const f32x4*)(base + off + bj * HALF + n * 16);
;                 if (m == 3) asm volatile("" : "+v"(acc[ai][0][0][0]), "+v"(acc[ai][0][0][1]), "+v"(acc[ai][1][0][0]), "+v"(acc[ai][1][0][1]), "+v"(acc[ai][0][1][0]), "+v"(acc[ai][0][1][1]), "+v"(acc[ai][1][1][0]), "+v"(acc[ai][1][1][1]),
;                                              "+v"(acc[ai][0][2][0]), "+v"(acc[ai][0][2][1]), "+v"(acc[ai][1][2][0]), "+v"(acc[ai][1][2][1]), "+v"(acc[ai][0][3][0]), "+v"(acc[ai][0][3][1]), "+v"(acc[ai][1][3][0]), "+v"(acc[ai][1][3][1]) :: "memory"); }
;         asm volatile("" ::: "memory");
; #pragma unroll
;         for (int ai = 0; ai < 2; ++ai)
; #pragma unroll
;             for (int m = 0; m < 4; ++m) { const int row = row0 + ai * HALF + m * 16; const size_t off = (size_t)row * ldc + col0; float sq = 0.f;
; #pragma unroll
;                 for (int bj = 0; bj < 2; ++bj)
; #pragma unroll
;                     for (int n = 0; n < 2; ++n) { const f32x4 v = acc[ai][bj][m][n]; *(f32x4*)(out + off + bj * HALF + n * 16) = v;
; template <class Epi, class Sched, bool ALIGN_EPI = false, bool SP2 = false>
; __device__ __forceinline__ void gemm_phase(PG8_LAS unsigned char* lds, const Gemm g, const Sched& S, const Epi& E) {
;     ...
;         if (!has_next) break;
; #pragma unroll
;         for (int a = 0; a < 2; ++a)
; #pragma unroll
;             for (int b = 0; b < 2; ++b)
; #pragma unroll
;                 for (int m = 0; m < 4; ++m)
; #pragma unroll
;                     for (int n = 0; n < 2; ++n) acc[a][b][m][n] = (f32x4){0.f, 0.f, 0.f, 0.f};
;         cur = nxt; cA = nA; cB = nB; ++ui;
;         if constexpr (ALIGN_EPI) { if (wr == 1) PG8_BAR; }
	v_pk_add_f32 v[62:63], v[62:63], v[162:163]
	v_pk_add_f32 v[60:61], v[60:61], v[160:161]
	s_waitcnt vmcnt(14)
	v_pk_add_f32 v[58:59], v[58:59], v[166:167]
	v_pk_add_f32 v[56:57], v[56:57], v[164:165]
	s_waitcnt vmcnt(13)
	v_pk_add_f32 v[42:43], v[42:43], v[170:171]
	v_pk_add_f32 v[40:41], v[40:41], v[168:169]
	s_waitcnt vmcnt(12)
	v_pk_add_f32 v[34:35], v[34:35], v[174:175]
	v_pk_add_f32 v[32:33], v[32:33], v[172:173]
	s_waitcnt vmcnt(11)
	v_pk_add_f32 v[54:55], v[54:55], v[178:179]
	v_pk_add_f32 v[52:53], v[52:53], v[176:177]
	s_waitcnt vmcnt(10)
	v_pk_add_f32 v[50:51], v[50:51], v[182:183]
	v_pk_add_f32 v[48:49], v[48:49], v[180:181]
	s_waitcnt vmcnt(9)
	v_pk_add_f32 v[26:27], v[26:27], v[186:187]
	v_pk_add_f32 v[24:25], v[24:25], v[184:185]
	s_waitcnt vmcnt(8)
	v_pk_add_f32 v[18:19], v[18:19], v[190:191]
	v_pk_add_f32 v[16:17], v[16:17], v[188:189]
	s_waitcnt vmcnt(7)
	v_pk_add_f32 v[46:47], v[46:47], v[194:195]
	v_pk_add_f32 v[44:45], v[44:45], v[192:193]
	s_waitcnt vmcnt(6)
	v_pk_add_f32 v[38:39], v[38:39], v[198:199]
	v_pk_add_f32 v[36:37], v[36:37], v[196:197]
	s_waitcnt vmcnt(5)
	v_pk_add_f32 v[14:15], v[14:15], v[202:203]
	v_pk_add_f32 v[12:13], v[12:13], v[200:201]
	s_waitcnt vmcnt(4)
	v_pk_add_f32 v[10:11], v[10:11], v[206:207]
	v_pk_add_f32 v[8:9], v[8:9], v[204:205]
	s_waitcnt vmcnt(3)
	v_pk_add_f32 v[30:31], v[30:31], v[210:211]
	v_pk_add_f32 v[28:29], v[28:29], v[208:209]
	s_waitcnt vmcnt(2)
	v_pk_add_f32 v[22:23], v[22:23], v[214:215]
	v_pk_add_f32 v[20:21], v[20:21], v[212:213]
	s_waitcnt vmcnt(1)
	v_pk_add_f32 v[6:7], v[6:7], v[218:219]
	v_pk_add_f32 v[4:5], v[4:5], v[216:217]
	s_waitcnt vmcnt(0)
	v_pk_add_f32 v[2:3], v[2:3], v[222:223]
	v_pk_add_f32 v[0:1], v[0:1], v[220:221]
	s_nop 0
	global_store_dwordx4 v[140:141], v[124:127], off
	global_store_dwordx4 v[140:141], v[120:123], off offset:64
	global_store_dwordx4 v[140:141], v[104:107], off offset:512
	global_store_dwordx4 v[140:141], v[96:99], off offset:576
	global_store_dwordx4 v[142:143], v[116:119], off
	global_store_dwordx4 v[142:143], v[112:115], off offset:64
	global_store_dwordx4 v[142:143], v[88:91], off offset:512
	global_store_dwordx4 v[142:143], v[80:83], off offset:576
	global_store_dwordx4 v[144:145], v[108:111], off
	global_store_dwordx4 v[144:145], v[100:103], off offset:64
	global_store_dwordx4 v[144:145], v[76:79], off offset:512
	global_store_dwordx4 v[144:145], v[72:75], off offset:576
	global_store_dwordx4 v[146:147], v[92:95], off
	global_store_dwordx4 v[146:147], v[84:87], off offset:64
	global_store_dwordx4 v[146:147], v[68:71], off offset:512
	global_store_dwordx4 v[146:147], v[64:67], off offset:576
	global_store_dwordx4 v[150:151], v[60:63], off
	global_store_dwordx4 v[148:149], v[56:59], off offset:64
	global_store_dwordx4 v[148:149], v[40:43], off offset:512
	global_store_dwordx4 v[148:149], v[32:35], off offset:576
	global_store_dwordx4 v[224:225], v[52:55], off
	global_store_dwordx4 v[152:153], v[48:51], off offset:64
	global_store_dwordx4 v[152:153], v[24:27], off offset:512
	global_store_dwordx4 v[152:153], v[16:19], off offset:576
	global_store_dwordx4 v[228:229], v[44:47], off
	global_store_dwordx4 v[226:227], v[36:39], off offset:64
	global_store_dwordx4 v[226:227], v[12:15], off offset:512
	global_store_dwordx4 v[226:227], v[8:11], off offset:576
	global_store_dwordx4 v[230:231], v[28:31], off
	global_store_dwordx4 v[232:233], v[20:23], off offset:64
	global_store_dwordx4 v[232:233], v[4:7], off offset:512
	global_store_dwordx4 v[232:233], v[0:3], off offset:576
	s_cbranch_vccnz .LBB0_1887
	s_andn2_b64 vcc, exec, s[10:11]
	s_cbranch_vccnz .LBB0_1886
	s_barrier
	s_branch .LBB0_1886
